# speedup vs baseline: 1.0362x; 1.0002x over previous
; DI unsigned pk_bf16(float lo, float hi) { unsigned r; asm("v_cvt_pk_bf16_f32 %0, %1, %2" : "=v"(r) : "v"(lo), "v"(hi)); return r; }
; DI int obid() { int b = blockIdx.x; asm volatile("" : "+s"(b)); return b; }
; DI f32x4 h4_to_f4(u32x2 t) { const h16x4 h = __builtin_bit_cast(h16x4, t); return (f32x4){(float)h[0], (float)h[1], (float)h[2], (float)h[3]}; }
; DI void phase_row(const Params& P, const void* xs, int sh, void* xd, int dh, int ln, int gl, int gidx, float wgt, int modl, int shidx, bool dry = false) {
;     ...
;     for (int row = obid() * 8 + w; row < T; row += gridDim.x * 8) {
;         const int b = row >= SEQ;
;         f32x4 v[4];
; #pragma unroll
;         for (int j = 0; j < 4; ++j) { const size_t e = (size_t)row * D + 4 * lane + 256 * j;
;             if (sh) v[j] = h4_to_f4(__builtin_nontemporal_load((const u32x2*)((const unsigned short*)xs + e))); else v[j] = __builtin_nontemporal_load((const f32x4*)((const float*)xs + e)); }
;     ...
;         if (modl >= 0) {
;             const float* shp = mod + (modl * 2 + b) * 9216 + shidx * 1024; const float* sc = shp + 1024;
; #pragma unroll
;             for (int j = 0; j < 4; ++j) { const f32x4 s4 = *(const f32x4*)(shp + 4 * lane + 256 * j), c4 = *(const f32x4*)(sc + 4 * lane + 256 * j);
;                 const f32x4 u = v[j] * (c4 + 1.f) + s4; u32x2 o; o.x = pk_bf16(u[0], u[1]); o.y = pk_bf16(u[2], u[3]);
;                 *(u32x2*)(U + (size_t)row * D + 4 * lane + 256 * j) = o; }
.LBB0_250:
	s_and_b64 vcc, exec, s[2:3]
	s_cbranch_vccz .LBB0_339
	s_waitcnt vmcnt(0)
	v_mov_b32_e32 v1, v195
	s_load_dwordx8 s[40:47], s[84:85], 0xc8
	v_ashrrev_i32_e32 v0, 6, v1
	s_mov_b32 s2, s28
	s_waitcnt lgkmcnt(0)
	s_mov_b64 s[4:5], s[46:47]
	s_mov_b64 s[8:9], s[46:47]
	s_nop 0
	v_lshl_add_u32 v0, s2, 3, v0
	v_cmp_gt_i32_e32 vcc, s75, v0
	s_and_saveexec_b64 s[2:3], vcc
	s_mov_b64 s[14:15], 0x1000
	s_cbranch_execz .LBB0_254
	v_lshlrev_b32_e32 v1, 2, v1
	v_and_b32_e32 v6, 0xfc, v1
	v_lshlrev_b32_e32 v184, 1, v6
	v_lshl_add_u64 v[2:3], s[8:9], 0, v[184:185]
	s_mov_b64 s[8:9], 0x5808000
	v_lshl_add_u64 v[2:3], v[2:3], 0, s[8:9]
	v_readlane_b32 s8, v244, 10
	s_add_u32 s4, s4, 0x5580000
	v_lshlrev_b32_e32 v184, 2, v6
	v_readlane_b32 s9, v244, 11
	s_addc_u32 s5, s5, 0
	v_lshlrev_b32_e32 v6, 2, v6
	v_lshl_add_u64 v[4:5], s[8:9], 0, v[184:185]
	s_mov_b64 s[8:9], 0
	s_mov_b64 s[100:101], 1
.LBB0_253:
	v_cmp_lt_i32_e32 vcc, s23, v0
	v_ashrrev_i32_e32 v1, 31, v0
	v_mov_b32_e32 v7, v185
	v_cndmask_b32_e32 v184, 0, v203, vcc
	v_lshl_add_u64 v[10:11], s[4:5], 0, v[184:185]
	v_lshlrev_b64 v[8:9], 12, v[0:1]
	v_lshl_add_u64 v[32:33], v[10:11], 0, v[6:7]
	v_lshl_add_u64 v[28:29], v[4:5], 0, v[8:9]
	s_cmp_eq_u64 vcc, s[100:101]
	s_cbranch_scc1 .Lrow1_keep
	s_mov_b64 s[100:101], vcc
	v_lshl_add_u64 v[36:37], v[32:33], 0, s[14:15]
	flat_load_dwordx4 v[40:43], v[36:37]
	flat_load_dwordx4 v[44:47], v[32:33]
	flat_load_dwordx4 v[48:51], v[36:37] offset:1024
	flat_load_dwordx4 v[52:55], v[32:33] offset:1024
	flat_load_dwordx4 v[56:59], v[36:37] offset:2048
	flat_load_dwordx4 v[60:63], v[32:33] offset:2048
	flat_load_dwordx4 v[64:67], v[36:37] offset:3072
	flat_load_dwordx4 v[68:71], v[32:33] offset:3072
.Lrow1_keep:
	v_lshlrev_b64 v[20:21], 11, v[0:1]
	global_load_dwordx4 v[12:15], v[28:29], off nt
	v_lshl_add_u64 v[34:35], v[2:3], 0, v[20:21]
	global_load_dwordx4 v[20:23], v[28:29], off offset:1024 nt
	global_load_dwordx4 v[24:27], v[28:29], off offset:2048 nt
	s_nop 0
	global_load_dwordx4 v[28:31], v[28:29], off offset:3072 nt
	v_add_u32_e32 v0, s70, v0
	v_cmp_lt_i32_e32 vcc, s20, v0
	s_or_b64 s[8:9], vcc, s[8:9]
	s_waitcnt vmcnt(0) lgkmcnt(0)
	v_pk_add_f32 v[8:9], v[40:41], 1.0 op_sel_hi:[1,0]
	v_pk_add_f32 v[10:11], v[42:43], 1.0 op_sel_hi:[1,0]
	v_pk_fma_f32 v[8:9], v[12:13], v[8:9], v[44:45]
	v_pk_fma_f32 v[10:11], v[14:15], v[10:11], v[46:47]
	v_cvt_pk_bf16_f32 v8, v8, v9
	s_nop 0
	v_cvt_pk_bf16_f32 v9, v10, v11
	s_nop 1
	flat_store_dwordx2 v[34:35], v[8:9]
	v_pk_add_f32 v[8:9], v[48:49], 1.0 op_sel_hi:[1,0]
	v_pk_add_f32 v[10:11], v[50:51], 1.0 op_sel_hi:[1,0]
	v_pk_fma_f32 v[8:9], v[20:21], v[8:9], v[52:53]
	v_pk_fma_f32 v[10:11], v[22:23], v[10:11], v[54:55]
	v_cvt_pk_bf16_f32 v8, v8, v9
	s_nop 0
	v_cvt_pk_bf16_f32 v9, v10, v11
	s_nop 1
	flat_store_dwordx2 v[34:35], v[8:9] offset:512
	v_pk_add_f32 v[8:9], v[56:57], 1.0 op_sel_hi:[1,0]
	v_pk_add_f32 v[10:11], v[58:59], 1.0 op_sel_hi:[1,0]
	v_pk_fma_f32 v[8:9], v[24:25], v[8:9], v[60:61]
	v_pk_fma_f32 v[10:11], v[26:27], v[10:11], v[62:63]
	v_cvt_pk_bf16_f32 v8, v8, v9
	s_nop 0
	v_cvt_pk_bf16_f32 v9, v10, v11
	s_nop 1
	flat_store_dwordx2 v[34:35], v[8:9] offset:1024
	v_pk_add_f32 v[8:9], v[64:65], 1.0 op_sel_hi:[1,0]
	v_pk_add_f32 v[10:11], v[66:67], 1.0 op_sel_hi:[1,0]
	v_pk_fma_f32 v[8:9], v[28:29], v[8:9], v[68:69]
	v_pk_fma_f32 v[10:11], v[30:31], v[10:11], v[70:71]
	v_cvt_pk_bf16_f32 v8, v8, v9
	s_nop 0
	v_cvt_pk_bf16_f32 v9, v10, v11
	s_nop 1
	flat_store_dwordx2 v[34:35], v[8:9] offset:1536
	s_andn2_b64 exec, exec, s[8:9]
	s_cbranch_execnz .LBB0_253
